# s15 + lever 4: one static s_setprio 1 for waves 4-7 over the whole attention phase (reset at the phase end)
# speedup vs baseline: 1.0084x; 1.0045x over previous
; __device__ __forceinline__ void phase_attn(char* lds_generic, int l, int wv) {
;     const Ctx c = fresh_ctx(wv); const bool last = (l == DEPTH - 1);
;     const bf16* Pb = (const bf16*)(c.ws + WS_P); const bf16* Qb = (const bf16*)(c.ws + WS_Q); const bf16* Kb = (const bf16*)(c.ws + WS_K); const bf16* Vb = (const bf16*)(c.ws + WS_V); bf16* Yb = (bf16*)(c.ws + WS_Y);
;     const int NU = 512 + (last ? 0 : 32);
;     for (int i = c.vcu; i < NU; i += c.G) {
.LBB0_594:
	s_and_b64 s[2:3], s[18:19], exec
	s_movk_i32 s2, 0x220
	s_cselect_b32 s46, s2, 0x200
	s_mov_b64 s[4:5], s[74:75]
	s_cmp_ge_i32 s1, s46
	s_cbranch_scc1 .LBB0_620
	s_cmp_lt_u32 s65, 0x100
	s_cbranch_scc1 .Lattn_old
	s_setprio 1
.Lattn_old:
	s_load_dwordx2 s[4:5], s[4:5], 0xa8
	v_add_u32_e32 v184, s65, v0
	s_waitcnt lgkmcnt(0)
	s_add_u32 s2, s4, 0x3fc00000
	s_addc_u32 s3, s5, 0
	s_add_u32 s34, s4, 0x41e00000
	s_addc_u32 s35, s5, 0
	s_add_u32 s36, s4, 0x42700000
	s_addc_u32 s37, s5, 0
	s_add_u32 s38, s4, 0x43000000
	s_addc_u32 s39, s5, 0
	s_add_u32 s10, s4, 0x42748000
	s_addc_u32 s11, s5, 0
	s_branch .LBB0_597

; __device__ __forceinline__ void xcd_barrier(const XcdBarrier& b, const bool t0) {
;     asm volatile("s_waitcnt vmcnt(0)" ::: "memory");
;     __syncthreads();
;     if (t0) {
;         unsigned* bar = b.bar;
;         __builtin_amdgcn_s_waitcnt(0);
.LBB0_620:
	s_setprio 0
	s_mov_b64 s[0:1], s[74:75]
	s_load_dwordx2 s[6:7], s[0:1], 0xa8
	v_readlane_b32 s0, v254, 10
	v_readlane_b32 s1, v254, 11
	s_mov_b64 s[8:9], 0
	s_and_b64 vcc, exec, s[0:1]
	s_getreg_b32 s0, hwreg(HW_REG_XCC_ID, 0, 4)
	s_cbranch_vccnz .LBB0_622
	v_mbcnt_lo_u32_b32 v0, -1, 0
	v_mbcnt_hi_u32_b32 v0, -1, v0
	s_nop 0
	v_cmp_eq_u32_e32 vcc, 0, v0
	s_and_b64 s[8:9], vcc, exec
